# scan item: static s_setprio 3 for the four helper waves (the step's limiting role) for the duration of the scan, reset to 0 at exit; on top of v40
# speedup vs baseline: 1.0145x; 1.0145x over previous
; #define LAS __attribute__((address_space(3)))
; DI void sh_load(const ScanH& k, int nc, u32x4 (&st)[14]) {
;     const size_t o8 = (size_t)nc * 8192; const int ht = k.ht;
; #pragma unroll
;     for (int i = 0; i < 4; ++i) { const int id = ht + 256 * i, r = id >> 4, cc = id & 15; st[i] = *(const u32x4*)(k.WC + o8 + r * 128 + cc * 8); st[4 + i] = *(const u32x4*)(k.QD + o8 + r * 128 + cc * 8); }
; #pragma unroll
;     for (int i = 0; i < 4; ++i) { const int id = ht + 256 * i, r = id >> 3, cc = id & 7; st[8 + i] = *(const u32x4*)(k.KD + o8 + r * 64 + cc * 8); }
; #pragma unroll
;     for (int i = 0; i < 2; ++i) { const int id = ht + 256 * i, r = id >> 3, cc = id & 7; st[12 + i] = *(const u32x4*)(k.AT + (size_t)nc * 4096 + r * 64 + cc * 8); }
; }
; DI void sh_store(const ScanH& k, int bf, const u32x4 (&st)[14]) {
;     LAS unsigned char* B_ = k.lds + bf * SC_BUF; const int ht = k.ht;
; #pragma unroll
;     for (int i = 0; i < 4; ++i) { const int id = ht + 256 * i, r = id >> 4, cc = id & 15;
;         *(LAS u32x2*)(B_ + SC_W + r * 264 + cc * 16) = (u32x2){st[i].x, st[i].y}; *(LAS u32x2*)(B_ + SC_W + r * 264 + cc * 16 + 8) = (u32x2){st[i].z, st[i].w};
;         *(LAS u32x2*)(B_ + SC_Q + r * 264 + cc * 16) = (u32x2){st[4 + i].x, st[4 + i].y}; *(LAS u32x2*)(B_ + SC_Q + r * 264 + cc * 16 + 8) = (u32x2){st[4 + i].z, st[4 + i].w}; }
; #pragma unroll
;     for (int i = 0; i < 4; ++i) { const int id = ht + 256 * i, r = id >> 3, cc = id & 7;
;         *(LAS u32x2*)(B_ + SC_K + r * 136 + cc * 16) = (u32x2){st[8 + i].x, st[8 + i].y}; *(LAS u32x2*)(B_ + SC_K + r * 136 + cc * 16 + 8) = (u32x2){st[8 + i].z, st[8 + i].w}; }
; #pragma unroll
;     for (int i = 0; i < 2; ++i) { const int id = ht + 256 * i, r = id >> 3, cc = id & 7;
;         *(LAS u32x2*)(B_ + SC_A + r * 136 + cc * 16) = (u32x2){st[12 + i].x, st[12 + i].y}; *(LAS u32x2*)(B_ + SC_A + r * 136 + cc * 16 + 8) = (u32x2){st[12 + i].z, st[12 + i].w}; }
; }
; DI void scan_item(LAS unsigned char* lds, const Ctx& c, int l, int bh) {
;     ...
;     if (w >= 4) {
;         ScanH k; k.lds = lds; k.b = b; k.h = h; k.ht = tid - 256; k.pt = k.ht >> 2; k.pseg = k.ht & 3;
;         k.WC = (const bf16_t*)(ws + WS_WC) + (size_t)bh * 128 * 8192; k.QD = (const bf16_t*)(ws + WS_QD) + (size_t)bh * 128 * 8192;
;         k.KD = (const bf16_t*)(ws + WS_KDT) + (size_t)bh * 128 * 8192; k.AT = (const bf16_t*)(ws + WS_AT) + (size_t)bh * 128 * 4096;
.LBB0_197:
	s_setprio 3
	v_add_u32_e32 v68, 0xffffff00, v208
	s_mov_b32 s41, s25
	s_waitcnt vmcnt(0)
	v_lshlrev_b32_e32 v34, 3, v68
	s_lshl_b64 s[10:11], s[40:41], 20
	s_lshl_b64 s[8:9], s[40:41], 21
	v_and_b32_e32 v2, 0xffffff80, v34
	s_add_u32 s4, s82, s8
	v_ashrrev_i32_e32 v3, 31, v2
	s_addc_u32 s5, s83, s9
	v_and_b32_e32 v58, 0x78, v34
	v_lshlrev_b64 v[134:135], 1, v[2:3]
	v_lshl_add_u64 v[2:3], s[4:5], 0, v[134:135]
	v_lshlrev_b32_e32 v0, 1, v58
	v_lshl_add_u64 v[2:3], v[2:3], 0, v[0:1]
	global_load_dwordx4 v[2:5], v[2:3], off
	s_add_u32 s6, s84, s8
	s_addc_u32 s7, s85, s9
	v_lshl_add_u64 v[6:7], s[6:7], 0, v[134:135]
	v_lshl_add_u64 v[6:7], v[6:7], 0, v[0:1]
	global_load_dwordx4 v[6:9], v[6:7], off
	v_add_u32_e32 v38, 0x800, v34
	v_and_b32_e32 v10, 0xffffff80, v38
	v_ashrrev_i32_e32 v11, 31, v10
	v_lshlrev_b64 v[136:137], 1, v[10:11]
	v_lshl_add_u64 v[10:11], s[4:5], 0, v[136:137]
	v_add_u32_e32 v42, 0x1000, v34
	v_lshl_add_u64 v[10:11], v[10:11], 0, v[0:1]
	v_and_b32_e32 v18, 0xffffff80, v42
	global_load_dwordx4 v[10:13], v[10:11], off
	v_lshl_add_u64 v[14:15], s[6:7], 0, v[136:137]
	v_ashrrev_i32_e32 v19, 31, v18
	v_add_u32_e32 v46, 0x1800, v34
	v_lshl_add_u64 v[14:15], v[14:15], 0, v[0:1]
	v_lshlrev_b64 v[138:139], 1, v[18:19]
	v_and_b32_e32 v26, 0xffffff80, v46
	global_load_dwordx4 v[14:17], v[14:15], off
	v_lshl_add_u64 v[18:19], s[4:5], 0, v[138:139]
	v_lshl_add_u64 v[22:23], s[6:7], 0, v[138:139]
	v_ashrrev_i32_e32 v27, 31, v26
	v_lshl_add_u64 v[18:19], v[18:19], 0, v[0:1]
	v_lshl_add_u64 v[22:23], v[22:23], 0, v[0:1]
	v_lshlrev_b64 v[140:141], 1, v[26:27]
	v_and_b32_e32 v60, 56, v34
	v_and_b32_e32 v34, 0xffffffc0, v34
	v_and_b32_e32 v38, 0xffffffc0, v38
	v_and_b32_e32 v42, 0xffffffc0, v42
	v_and_b32_e32 v46, 0xffffffc0, v46
	s_add_u32 s8, s86, s8
	global_load_dwordx4 v[18:21], v[18:19], off
	v_lshl_add_u64 v[26:27], s[4:5], 0, v[140:141]
	global_load_dwordx4 v[22:25], v[22:23], off
	v_ashrrev_i32_e32 v35, 31, v34
	v_ashrrev_i32_e32 v39, 31, v38
	v_ashrrev_i32_e32 v43, 31, v42
	v_ashrrev_i32_e32 v47, 31, v46
	s_addc_u32 s9, s87, s9
	v_lshl_add_u64 v[26:27], v[26:27], 0, v[0:1]
	v_lshlrev_b64 v[142:143], 1, v[34:35]
	v_lshlrev_b64 v[144:145], 1, v[38:39]
	v_lshlrev_b64 v[146:147], 1, v[42:43]
	v_lshlrev_b64 v[148:149], 1, v[46:47]
	s_add_u32 s10, s88, s10
	global_load_dwordx4 v[26:29], v[26:27], off
	v_lshl_add_u64 v[30:31], s[6:7], 0, v[140:141]
	v_lshl_add_u64 v[34:35], s[8:9], 0, v[142:143]
	v_lshlrev_b32_e32 v54, 1, v60
	v_mov_b32_e32 v55, v1
	v_lshl_add_u64 v[38:39], s[8:9], 0, v[144:145]
	v_lshl_add_u64 v[42:43], s[8:9], 0, v[146:147]
	v_lshl_add_u64 v[46:47], s[8:9], 0, v[148:149]
	s_addc_u32 s11, s89, s11
	v_lshl_add_u64 v[30:31], v[30:31], 0, v[0:1]
	v_lshl_add_u64 v[34:35], v[34:35], 0, v[54:55]
	v_lshl_add_u64 v[38:39], v[38:39], 0, v[54:55]
	v_lshl_add_u64 v[42:43], v[42:43], 0, v[54:55]
	v_lshl_add_u64 v[46:47], v[46:47], 0, v[54:55]
	global_load_dwordx4 v[30:33], v[30:31], off
	v_lshl_add_u64 v[50:51], s[10:11], 0, v[142:143]
	global_load_dwordx4 v[34:37], v[34:35], off
	v_lshl_add_u64 v[50:51], v[50:51], 0, v[54:55]
	global_load_dwordx4 v[38:41], v[38:39], off
	v_lshl_add_u64 v[56:57], s[10:11], 0, v[144:145]
	global_load_dwordx4 v[42:45], v[42:43], off
	v_lshl_add_u64 v[56:57], v[56:57], 0, v[54:55]
	global_load_dwordx4 v[46:49], v[46:47], off
	v_ashrrev_i32_e32 v63, 4, v68
	global_load_dwordx4 v[50:53], v[50:51], off
	s_movk_i32 s14, 0x108
	global_load_dwordx4 v[64:67], v[56:57], off
	v_lshlrev_b32_e32 v56, 4, v68
	v_and_b32_e32 v62, 0xf0, v56
	v_add_u32_e32 v57, 0, v62
	s_waitcnt vmcnt(0)
	v_mul_lo_u32 v158, v63, s14
	v_add_u32_e32 v159, v57, v158
	ds_write2_b64 v159, v[2:3], v[4:5] offset1:1
	v_ashrrev_i32_e32 v2, 4, v208
	v_mul_lo_u32 v161, v2, s14
	v_add_u32_e32 v2, 0x100, v208
	v_ashrrev_i32_e32 v3, 4, v2
	v_mul_lo_u32 v164, v3, s14
	v_add_u32_e32 v3, 0x200, v208
	v_ashrrev_i32_e32 v4, 4, v3
	v_add_u32_e32 v160, 0x4200, v159
	v_mul_lo_u32 v167, v4, s14
	s_movk_i32 s14, 0x88
	v_lshrrev_b32_e32 v2, 3, v2
	ds_write2_b64 v160, v[6:7], v[8:9] offset1:1
	v_and_b32_e32 v63, 0x70, v56
	v_lshrrev_b32_e32 v5, 3, v68
	v_lshrrev_b32_e32 v6, 3, v208
	v_mul_lo_u32 v174, v2, s14
	v_lshrrev_b32_e32 v2, 3, v3
	v_add_u32_e32 v4, 0, v63
	v_mul_lo_u32 v170, v5, s14
	v_mul_lo_u32 v172, v6, s14
	s_mov_b32 s15, 0x8400
	v_mul_lo_u32 v176, v2, s14
	s_add_u32 s14, s4, 0x4000
	v_add3_u32 v175, v4, v174, s15
	v_add3_u32 v177, v4, v176, s15
	s_addc_u32 s15, s5, 0
	s_add_u32 s42, s6, 0x4000
	v_add_u32_e32 v6, v4, v172
	s_addc_u32 s43, s7, 0
	v_add_u32_e32 v173, 0x8400, v6
	v_add_u32_e32 v179, 0xc800, v6
	v_lshl_add_u64 v[2:3], s[14:15], 0, v[134:135]
	v_lshl_add_u64 v[6:7], s[42:43], 0, v[134:135]
	v_add_u32_e32 v162, v57, v161
	v_add_u32_e32 v5, v4, v170
	v_lshl_add_u64 v[2:3], v[2:3], 0, v[0:1]
	v_lshl_add_u64 v[6:7], v[6:7], 0, v[0:1]
	ds_write2_b64 v162, v[10:11], v[12:13] offset1:1
	v_add_u32_e32 v171, 0x8400, v5
	v_add_u32_e32 v178, 0xc800, v5
	global_load_dwordx4 v[2:5], v[2:3], off
	v_add_u32_e32 v163, 0x4200, v162
	global_load_dwordx4 v[10:13], v[6:7], off
	v_lshl_add_u64 v[6:7], s[14:15], 0, v[136:137]
	v_lshl_add_u64 v[6:7], v[6:7], 0, v[0:1]
	v_add_u32_e32 v165, v57, v164
	global_load_dwordx4 v[6:9], v[6:7], off
	ds_write2_b64 v163, v[14:15], v[16:17] offset1:1
	v_lshl_add_u64 v[14:15], s[42:43], 0, v[136:137]
	v_add_u32_e32 v166, 0x4200, v165
	v_lshl_add_u64 v[14:15], v[14:15], 0, v[0:1]
	ds_write2_b64 v165, v[18:19], v[20:21] offset1:1
	global_load_dwordx4 v[18:21], v[14:15], off
	ds_write2_b64 v166, v[22:23], v[24:25] offset1:1
	v_lshl_add_u64 v[14:15], s[14:15], 0, v[138:139]
	v_lshl_add_u64 v[22:23], s[42:43], 0, v[138:139]
; DI void sh_load(const ScanH& k, int nc, u32x4 (&st)[14]) {
;     const size_t o8 = (size_t)nc * 8192; const int ht = k.ht;
; #pragma unroll
;     for (int i = 0; i < 4; ++i) { const int id = ht + 256 * i, r = id >> 4, cc = id & 15; st[i] = *(const u32x4*)(k.WC + o8 + r * 128 + cc * 8); st[4 + i] = *(const u32x4*)(k.QD + o8 + r * 128 + cc * 8); }
; #pragma unroll
;     for (int i = 0; i < 4; ++i) { const int id = ht + 256 * i, r = id >> 3, cc = id & 7; st[8 + i] = *(const u32x4*)(k.KD + o8 + r * 64 + cc * 8); }
; #pragma unroll
;     for (int i = 0; i < 2; ++i) { const int id = ht + 256 * i, r = id >> 3, cc = id & 7; st[12 + i] = *(const u32x4*)(k.AT + (size_t)nc * 4096 + r * 64 + cc * 8); }
; }
; DI void sh_store(const ScanH& k, int bf, const u32x4 (&st)[14]) {
;     LAS unsigned char* B_ = k.lds + bf * SC_BUF; const int ht = k.ht;
; #pragma unroll
;     for (int i = 0; i < 4; ++i) { const int id = ht + 256 * i, r = id >> 4, cc = id & 15;
;         *(LAS u32x2*)(B_ + SC_W + r * 264 + cc * 16) = (u32x2){st[i].x, st[i].y}; *(LAS u32x2*)(B_ + SC_W + r * 264 + cc * 16 + 8) = (u32x2){st[i].z, st[i].w};
;         *(LAS u32x2*)(B_ + SC_Q + r * 264 + cc * 16) = (u32x2){st[4 + i].x, st[4 + i].y}; *(LAS u32x2*)(B_ + SC_Q + r * 264 + cc * 16 + 8) = (u32x2){st[4 + i].z, st[4 + i].w}; }
; #pragma unroll
;     for (int i = 0; i < 4; ++i) { const int id = ht + 256 * i, r = id >> 3, cc = id & 7;
;         *(LAS u32x2*)(B_ + SC_K + r * 136 + cc * 16) = (u32x2){st[8 + i].x, st[8 + i].y}; *(LAS u32x2*)(B_ + SC_K + r * 136 + cc * 16 + 8) = (u32x2){st[8 + i].z, st[8 + i].w}; }
; #pragma unroll
;     for (int i = 0; i < 2; ++i) { const int id = ht + 256 * i, r = id >> 3, cc = id & 7;
;         *(LAS u32x2*)(B_ + SC_A + r * 136 + cc * 16) = (u32x2){st[12 + i].x, st[12 + i].y}; *(LAS u32x2*)(B_ + SC_A + r * 136 + cc * 16 + 8) = (u32x2){st[12 + i].z, st[12 + i].w}; }
; }
; DI void scan_helper_step(const ScanH& k, int n, u32x4 (&stL)[14], const u32x4 (&stS)[14]) {
;     LAS unsigned char* lds = k.lds; const int bf = n & 1, tokb = k.b * SEQ + n * 64;
;     u32x4 zz[4];
;     { const bf16_t* zp = k.Zg + (size_t)(tokb + k.pt) * 512 + k.h * 128 + 32 * k.pseg;
; #pragma unroll
;       for (int i = 0; i < 4; ++i) zz[i] = *(const u32x4*)(zp + 8 * i); }
;     sh_load(k, n + 2 < 128 ? n + 2 : 127, stL);
;     sh_store(k, bf ^ 1, stS);
;     SC_RAW_BARRIER();
	v_add_u32_e32 v168, v57, v167
	v_lshl_add_u64 v[14:15], v[14:15], 0, v[0:1]
	v_lshl_add_u64 v[22:23], v[22:23], 0, v[0:1]
	ds_write2_b64 v168, v[26:27], v[28:29] offset1:1
	global_load_dwordx4 v[14:17], v[14:15], off
	v_add_u32_e32 v169, 0x4200, v168
	global_load_dwordx4 v[26:29], v[22:23], off
	v_lshl_add_u64 v[22:23], s[14:15], 0, v[140:141]
	s_add_u32 s14, s8, 0x4000
	v_lshl_add_u64 v[22:23], v[22:23], 0, v[0:1]
	s_addc_u32 s15, s9, 0
	global_load_dwordx4 v[22:25], v[22:23], off
	ds_write2_b64 v169, v[30:31], v[32:33] offset1:1
	ds_write2_b64 v171, v[34:35], v[36:37] offset1:1
	ds_write2_b64 v173, v[38:39], v[40:41] offset1:1
	ds_write2_b64 v175, v[42:43], v[44:45] offset1:1
	ds_write2_b64 v177, v[46:47], v[48:49] offset1:1
	v_lshl_add_u64 v[34:35], s[14:15], 0, v[142:143]
	v_lshl_add_u64 v[38:39], s[14:15], 0, v[144:145]
	v_lshl_add_u64 v[42:43], s[14:15], 0, v[146:147]
	v_lshl_add_u64 v[46:47], s[14:15], 0, v[148:149]
	s_add_u32 s14, s10, 0x2000
	s_addc_u32 s15, s11, 0
	ds_write2_b64 v178, v[50:51], v[52:53] offset1:1
	v_lshl_add_u64 v[30:31], s[42:43], 0, v[140:141]
	v_lshl_add_u64 v[50:51], s[14:15], 0, v[142:143]
	v_lshl_add_u64 v[56:57], s[14:15], 0, v[144:145]
	v_lshl_add_u64 v[30:31], v[30:31], 0, v[0:1]
	v_lshl_add_u64 v[34:35], v[34:35], 0, v[54:55]
	v_lshl_add_u64 v[38:39], v[38:39], 0, v[54:55]
	v_lshl_add_u64 v[42:43], v[42:43], 0, v[54:55]
	v_lshl_add_u64 v[46:47], v[46:47], 0, v[54:55]
	v_lshl_add_u64 v[50:51], v[50:51], 0, v[54:55]
	v_lshl_add_u64 v[54:55], v[56:57], 0, v[54:55]
	global_load_dwordx4 v[30:33], v[30:31], off
	s_lshl_b32 s14, s94, 12
	global_load_dwordx4 v[34:37], v[34:35], off
	v_ashrrev_i32_e32 v61, 2, v68
	global_load_dwordx4 v[38:41], v[38:39], off
	s_and_b32 s14, s14, 0x7fffe000
	global_load_dwordx4 v[42:45], v[42:43], off
	v_add_u32_e32 v150, s14, v61
	global_load_dwordx4 v[46:49], v[46:47], off
	s_lshl_b32 s14, s40, 8
	global_load_dwordx4 v[50:53], v[50:51], off
	s_and_b32 s24, s14, 0x300
	global_load_dwordx4 v[54:57], v[54:55], off
	v_and_b32_e32 v59, 3, v208
	s_add_u32 s14, s90, s24
	ds_write2_b64 v179, v[64:65], v[66:67] offset1:1
	s_addc_u32 s15, s91, 0
	v_lshlrev_b32_e32 v64, 6, v59
	v_mov_b32_e32 v65, v1
	v_lshl_add_u64 v[152:153], s[14:15], 0, v[64:65]
	v_ashrrev_i32_e32 v237, 31, v150
	v_mov_b32_e32 v236, v150
	v_lshlrev_b64 v[236:237], 10, v[236:237]
	v_lshl_add_u64 v[236:237], v[152:153], 0, v[236:237]
	global_load_dwordx4 v[114:117], v[236:237], off offset:48
	global_load_dwordx4 v[118:121], v[236:237], off offset:32
	global_load_dwordx4 v[122:125], v[236:237], off offset:16
	global_load_dwordx4 v[126:129], v[236:237], off
	v_readlane_b32 s14, v254, 0
	v_lshlrev_b32_e32 v59, 7, v59
	s_mov_b32 s40, -2
	v_add_u32_e32 v180, s14, v62
	v_readlane_b32 s14, v254, 1
	v_lshlrev_b32_e32 v156, 1, v60
	s_waitcnt lgkmcnt(0)
	v_add_u32_e32 v181, s14, v63
	v_readlane_b32 s14, v254, 2
	s_barrier
	s_nop 0
	v_add_u32_e32 v182, s14, v63
	s_add_u32 s14, s92, s24
	s_addc_u32 s15, s93, 0
	v_lshl_add_u64 v[154:155], s[14:15], 0, v[64:65]
	s_movk_i32 s14, 0x110
	v_mul_lo_u32 v0, v61, s14
	s_add_i32 s14, 0, 0x1d400
	v_add_u32_e32 v61, s14, v0
	v_readlane_b32 s14, v254, 3
	v_add_u32_e32 v183, v61, v64
	s_nop 0
	v_add_u32_e32 v62, s14, v0
	v_lshlrev_b32_e32 v0, 1, v58
	v_add_u32_e32 v58, 0, v59
	v_add_u32_e32 v184, 0x25e00, v58
	v_add_u32_e32 v185, v62, v64
.LBB0_198:
	v_ashrrev_i32_e32 v151, 31, v150
	v_add_u32_e32 v58, 64, v150
	v_ashrrev_i32_e32 v59, 31, v58
	v_lshlrev_b64 v[58:59], 10, v[58:59]
	v_lshl_add_u64 v[58:59], v[152:153], 0, v[58:59]
	global_load_dwordx4 v[236:239], v[58:59], off offset:48
	global_load_dwordx4 v[240:243], v[58:59], off offset:32
	global_load_dwordx4 v[244:247], v[58:59], off offset:16
	global_load_dwordx4 v[248:251], v[58:59], off
	s_add_i32 s24, s40, 2
	v_add_u32_e32 v186, 0xea00, v159
	s_min_u32 s14, s24, 0x7d
	s_waitcnt vmcnt(17)
	ds_write2_b64 v186, v[2:3], v[4:5] offset1:1
	v_add_u32_e32 v2, v180, v158
	s_lshl_b32 s41, s14, 13
	s_waitcnt vmcnt(16)
	ds_write2_b64 v2, v[10:11], v[12:13] offset1:1
	v_add_u32_e32 v2, 0xea00, v162
	s_addk_i32 s41, 0x4000
	s_waitcnt vmcnt(15)
	ds_write2_b64 v2, v[6:7], v[8:9] offset1:1
	v_add_u32_e32 v2, v180, v161
	s_lshl_b32 s44, s41, 1
	s_waitcnt vmcnt(14)
	ds_write2_b64 v2, v[18:19], v[20:21] offset1:1
	v_add_u32_e32 v2, 0xea00, v165
	s_add_u32 s14, s4, s44
	s_waitcnt vmcnt(13)
	ds_write2_b64 v2, v[14:15], v[16:17] offset1:1
	v_add_u32_e32 v2, v180, v164
	s_addc_u32 s15, s5, 0
	s_waitcnt vmcnt(12)
	ds_write2_b64 v2, v[26:27], v[28:29] offset1:1
	v_add_u32_e32 v2, 0xea00, v168
	s_add_u32 s42, s6, s44
	s_waitcnt vmcnt(11)
	ds_write2_b64 v2, v[22:23], v[24:25] offset1:1
	v_add_u32_e32 v2, v180, v167
	s_addc_u32 s43, s7, 0
	s_waitcnt vmcnt(10)
	ds_write2_b64 v2, v[30:31], v[32:33] offset1:1
	v_add_u32_e32 v2, v181, v170
	v_lshl_add_u64 v[58:59], s[14:15], 0, v[134:135]
	v_lshl_add_u64 v[66:67], s[14:15], 0, v[136:137]
	v_lshl_add_u64 v[74:75], s[14:15], 0, v[138:139]
	v_lshl_add_u64 v[82:83], s[14:15], 0, v[140:141]
	s_add_u32 s14, s8, s44
	s_waitcnt vmcnt(9)
	ds_write2_b64 v2, v[34:35], v[36:37] offset1:1
	v_add_u32_e32 v2, v181, v172
	s_addc_u32 s15, s9, 0
	s_waitcnt vmcnt(8)
	ds_write2_b64 v2, v[38:39], v[40:41] offset1:1
	v_add_u32_e32 v2, v181, v174
	v_lshl_add_u64 v[90:91], s[14:15], 0, v[142:143]
	v_lshl_add_u64 v[94:95], s[14:15], 0, v[144:145]
	v_lshl_add_u64 v[98:99], s[14:15], 0, v[146:147]
	v_lshl_add_u64 v[102:103], s[14:15], 0, v[148:149]
	s_add_u32 s14, s10, s41
	s_waitcnt vmcnt(7)
	ds_write2_b64 v2, v[42:43], v[44:45] offset1:1
	v_add_u32_e32 v2, v181, v176
	s_addc_u32 s15, s11, 0
	s_waitcnt vmcnt(6)
; #define LAS __attribute__((address_space(3)))
; DI float lo_bf(unsigned u) { return __uint_as_float(u << 16); }
; DI float hi_bf(unsigned u) { return __uint_as_float(u & 0xffff0000u); }
; #define SC_RAW_BARRIER() do { asm volatile("s_waitcnt lgkmcnt(0)" ::: "memory"); __builtin_amdgcn_s_barrier(); asm volatile("" ::: "memory"); } while (0)
; DI void scan_helper_step(const ScanH& k, int n, u32x4 (&stL)[14], const u32x4 (&stS)[14]) {
;     LAS unsigned char* lds = k.lds; const int bf = n & 1, tokb = k.b * SEQ + n * 64;
;     u32x4 zz[4];
;     { const bf16_t* zp = k.Zg + (size_t)(tokb + k.pt) * 512 + k.h * 128 + 32 * k.pseg;
; #pragma unroll
;       for (int i = 0; i < 4; ++i) zz[i] = *(const u32x4*)(zp + 8 * i); }
;     sh_load(k, n + 2 < 128 ? n + 2 : 127, stL);
;     sh_store(k, bf ^ 1, stS);
;     SC_RAW_BARRIER();
;     const LAS unsigned char* ob = lds + SC_O + bf * SC_OSZ + k.pt * 272 + k.pseg * 64;
;     const LAS float* gmL = (const LAS float*)(lds + SC_O + 2 * SC_OSZ + 512) + 32 * k.pseg;
;     u32x4 ov4[4];
; #pragma unroll
;     for (int i = 0; i < 4; ++i) ov4[i] = *(const LAS u32x4*)(ob + 16 * i);
;     float ss = 0.f;
; #pragma unroll
;     for (int i = 0; i < 4; ++i)
; #pragma unroll
;         for (int j = 0; j < 4; ++j) { const float a = lo_bf(ov4[i][j]), b2 = hi_bf(ov4[i][j]); ss += a * a + b2 * b2; }
;     ss += __shfl_xor(ss, 1); ss += __shfl_xor(ss, 2);
;     const float rs = __builtin_amdgcn_rsqf(ss * (1.f / 128.f) + RMS_EPS);
	ds_write2_b64 v2, v[46:47], v[48:49] offset1:1
	v_add_u32_e32 v2, v182, v170
	v_lshl_add_u64 v[62:63], s[42:43], 0, v[134:135]
	v_lshl_add_u64 v[70:71], s[42:43], 0, v[136:137]
	v_lshl_add_u64 v[78:79], s[42:43], 0, v[138:139]
	v_lshl_add_u64 v[86:87], s[42:43], 0, v[140:141]
	v_mov_b32_e32 v157, v1
	v_lshl_add_u64 v[106:107], s[14:15], 0, v[142:143]
	v_lshl_add_u64 v[110:111], s[14:15], 0, v[144:145]
	s_waitcnt vmcnt(5)
	ds_write2_b64 v2, v[50:51], v[52:53] offset1:1
	v_add_u32_e32 v2, v182, v172
	v_lshl_add_u64 v[58:59], v[58:59], 0, v[0:1]
	v_lshl_add_u64 v[62:63], v[62:63], 0, v[0:1]
	v_lshl_add_u64 v[66:67], v[66:67], 0, v[0:1]
	v_lshl_add_u64 v[70:71], v[70:71], 0, v[0:1]
	v_lshl_add_u64 v[74:75], v[74:75], 0, v[0:1]
	v_lshl_add_u64 v[78:79], v[78:79], 0, v[0:1]
	v_lshl_add_u64 v[82:83], v[82:83], 0, v[0:1]
	v_lshl_add_u64 v[86:87], v[86:87], 0, v[0:1]
	v_lshl_add_u64 v[90:91], v[90:91], 0, v[156:157]
	v_lshl_add_u64 v[94:95], v[94:95], 0, v[156:157]
	v_lshl_add_u64 v[98:99], v[98:99], 0, v[156:157]
	v_lshl_add_u64 v[102:103], v[102:103], 0, v[156:157]
	v_lshl_add_u64 v[106:107], v[106:107], 0, v[156:157]
	v_lshl_add_u64 v[110:111], v[110:111], 0, v[156:157]
	s_waitcnt vmcnt(4)
	ds_write2_b64 v2, v[54:55], v[56:57] offset1:1
	global_load_dwordx4 v[58:61], v[58:59], off
	s_add_i32 s14, s40, 3
	global_load_dwordx4 v[62:65], v[62:63], off
	s_min_u32 s14, s14, 0x7d
	global_load_dwordx4 v[66:69], v[66:67], off
	s_lshl_b32 s14, s14, 13
	global_load_dwordx4 v[70:73], v[70:71], off
	v_lshlrev_b32_e32 v228, 16, v118
	global_load_dwordx4 v[74:77], v[74:75], off
	v_and_b32_e32 v229, 0xffff0000, v118
	global_load_dwordx4 v[78:81], v[78:79], off
	v_lshlrev_b32_e32 v56, 16, v128
	global_load_dwordx4 v[82:85], v[82:83], off
	v_and_b32_e32 v57, 0xffff0000, v128
	global_load_dwordx4 v[86:89], v[86:87], off
	v_lshlrev_b32_e32 v192, 16, v127
	global_load_dwordx4 v[90:93], v[90:91], off
	v_and_b32_e32 v193, 0xffff0000, v127
	global_load_dwordx4 v[94:97], v[94:95], off
	v_lshlrev_b32_e32 v202, 16, v126
	global_load_dwordx4 v[98:101], v[98:99], off
	v_and_b32_e32 v203, 0xffff0000, v126
	global_load_dwordx4 v[102:105], v[102:103], off
	v_lshlrev_b32_e32 v126, 16, v129
	global_load_dwordx4 v[106:109], v[106:107], off
	v_and_b32_e32 v127, 0xffff0000, v129
	global_load_dwordx4 v[110:113], v[110:111], off
	s_waitcnt lgkmcnt(0)
	s_barrier
	ds_read_b128 v[14:17], v183
	ds_read_b128 v[18:21], v183 offset:16
	ds_read_b128 v[22:25], v183 offset:32
	ds_read_b128 v[2:5], v183 offset:48
	v_lshlrev_b32_e32 v210, 16, v124
	s_waitcnt lgkmcnt(3)
	v_lshlrev_b32_e32 v188, 16, v15
	v_and_b32_e32 v189, 0xffff0000, v15
	s_waitcnt lgkmcnt(1)
	v_and_b32_e32 v13, 0xffff0000, v25
	v_and_b32_e32 v12, 0xffff0000, v24
	v_lshlrev_b32_e32 v11, 16, v25
	v_lshlrev_b32_e32 v10, 16, v24
	v_pk_mul_f32 v[6:7], v[12:13], v[12:13]
	s_waitcnt lgkmcnt(0)
	v_and_b32_e32 v9, 0xffff0000, v3
	v_and_b32_e32 v8, 0xffff0000, v2
	v_pk_fma_f32 v[40:41], v[10:11], v[10:11], v[6:7]
	v_lshlrev_b32_e32 v7, 16, v3
	v_lshlrev_b32_e32 v6, 16, v2
	v_pk_mul_f32 v[2:3], v[8:9], v[8:9]
	v_lshlrev_b32_e32 v198, 16, v14
	v_pk_fma_f32 v[42:43], v[6:7], v[6:7], v[2:3]
	v_lshlrev_b32_e32 v3, 16, v5
	v_lshlrev_b32_e32 v2, 16, v4
	v_and_b32_e32 v5, 0xffff0000, v5
	v_and_b32_e32 v4, 0xffff0000, v4
	v_pk_mul_f32 v[24:25], v[4:5], v[4:5]
	v_and_b32_e32 v199, 0xffff0000, v14
	v_pk_fma_f32 v[44:45], v[2:3], v[2:3], v[24:25]
	v_and_b32_e32 v25, 64, v230
	v_xor_b32_e32 v24, 1, v230
	v_add_u32_e32 v25, 64, v25
	v_cmp_lt_i32_e32 vcc, v24, v25
	v_lshlrev_b32_e32 v52, 16, v16
	v_and_b32_e32 v53, 0xffff0000, v16
	v_cndmask_b32_e32 v24, v230, v24, vcc
	v_lshlrev_b32_e32 v186, 2, v24
	v_xor_b32_e32 v24, 2, v230
	v_cmp_lt_i32_e32 vcc, v24, v25
	v_pk_mul_f32 v[190:191], v[188:189], v[188:189]
	v_pk_mul_f32 v[200:201], v[198:199], v[198:199]
	v_cndmask_b32_e32 v24, v230, v24, vcc
	v_lshlrev_b32_e32 v187, 2, v24
	v_lshlrev_b64 v[24:25], 11, v[150:151]
	v_lshlrev_b32_e32 v48, 16, v17
	v_and_b32_e32 v49, 0xffff0000, v17
	v_pk_mul_f32 v[54:55], v[52:53], v[52:53]
	v_add_f32_e32 v118, v190, v191
	v_add_f32_e32 v151, v200, v201
	v_pk_mul_f32 v[50:51], v[48:49], v[48:49]
	v_lshlrev_b32_e32 v218, 16, v18
	v_and_b32_e32 v219, 0xffff0000, v18
	v_add_f32_e32 v118, v151, v118
	v_add_f32_e32 v54, v54, v55
	v_lshlrev_b32_e32 v212, 16, v19
	v_and_b32_e32 v213, 0xffff0000, v19
	v_pk_mul_f32 v[18:19], v[218:219], v[218:219]
	v_add_f32_e32 v54, v54, v118
	v_add_f32_e32 v50, v50, v51
	v_lshlrev_b32_e32 v208, 16, v20
	v_and_b32_e32 v209, 0xffff0000, v20
	v_pk_mul_f32 v[214:215], v[212:213], v[212:213]
	v_add_f32_e32 v50, v50, v54
	v_add_f32_e32 v18, v18, v19
	v_lshlrev_b32_e32 v128, 16, v21
	v_and_b32_e32 v129, 0xffff0000, v21
	v_pk_mul_f32 v[20:21], v[208:209], v[208:209]
	v_add_f32_e32 v18, v18, v50
	v_add_f32_e32 v19, v214, v215
	v_pk_mul_f32 v[204:205], v[128:129], v[128:129]
	v_lshlrev_b32_e32 v224, 16, v22
	v_and_b32_e32 v225, 0xffff0000, v22
	v_add_f32_e32 v18, v19, v18
	v_add_f32_e32 v19, v20, v21
	v_and_b32_e32 v211, 0xffff0000, v124
	v_lshlrev_b32_e32 v216, 16, v123
	v_and_b32_e32 v217, 0xffff0000, v123
	v_lshlrev_b32_e32 v220, 16, v122
	v_and_b32_e32 v221, 0xffff0000, v122
	v_lshlrev_b32_e32 v122, 16, v125
	v_and_b32_e32 v123, 0xffff0000, v125
	v_lshlrev_b32_e32 v124, 16, v23
	v_and_b32_e32 v125, 0xffff0000, v23
	v_pk_mul_f32 v[22:23], v[224:225], v[224:225]
	v_add_f32_e32 v18, v19, v18
	v_add_f32_e32 v19, v204, v205
	v_pk_mul_f32 v[222:223], v[124:125], v[124:125]
	v_add_f32_e32 v18, v19, v18
	v_add_f32_e32 v19, v22, v23
	v_add_f32_e32 v18, v19, v18
	v_add_f32_e32 v19, v222, v223
	v_add_f32_e32 v18, v19, v18
	v_add_f32_e32 v18, v40, v18
	v_add_f32_e32 v18, v41, v18
	v_add_f32_e32 v18, v42, v18
	v_add_f32_e32 v18, v43, v18
	v_add_f32_e32 v18, v44, v18
	v_add_f32_e32 v18, v45, v18
	s_nop 1
	v_mov_b32_dpp v19, v18 quad_perm:[1,0,3,2] row_mask:0xf bank_mask:0xf
	v_lshl_add_u64 v[46:47], v[154:155], 0, v[24:25]
	ds_read_b128 v[24:27], v184
	ds_read_b128 v[28:31], v184 offset:16
	ds_read_b128 v[32:35], v184 offset:32
	ds_read_b128 v[36:39], v184 offset:48
	ds_read_b128 v[14:17], v184 offset:64
	ds_read_b128 v[130:133], v184 offset:80
	ds_read_b128 v[194:197], v184 offset:96
	ds_read_b128 v[232:235], v184 offset:112
	s_add_i32 s42, s14, 0x4000
	s_waitcnt lgkmcnt(5)
; DI unsigned pk2(float lo, float hi) { f32x2 v = {lo, hi}; bf16x2_t b = __builtin_convertvector(v, bf16x2_t); return __builtin_bit_cast(unsigned, b); }
; DI float lo_bf(unsigned u) { return __uint_as_float(u << 16); }
; DI float hi_bf(unsigned u) { return __uint_as_float(u & 0xffff0000u); }
; DI void sh_load(const ScanH& k, int nc, u32x4 (&st)[14]) {
;     const size_t o8 = (size_t)nc * 8192; const int ht = k.ht;
; #pragma unroll
;     for (int i = 0; i < 4; ++i) { const int id = ht + 256 * i, r = id >> 4, cc = id & 15; st[i] = *(const u32x4*)(k.WC + o8 + r * 128 + cc * 8); st[4 + i] = *(const u32x4*)(k.QD + o8 + r * 128 + cc * 8); }
; #pragma unroll
;     for (int i = 0; i < 4; ++i) { const int id = ht + 256 * i, r = id >> 3, cc = id & 7; st[8 + i] = *(const u32x4*)(k.KD + o8 + r * 64 + cc * 8); }
; #pragma unroll
;     for (int i = 0; i < 2; ++i) { const int id = ht + 256 * i, r = id >> 3, cc = id & 7; st[12 + i] = *(const u32x4*)(k.AT + (size_t)nc * 4096 + r * 64 + cc * 8); }
; }
; DI void scan_helper_step(const ScanH& k, int n, u32x4 (&stL)[14], const u32x4 (&stS)[14]) {
;     ...
;     const float rs = __builtin_amdgcn_rsqf(ss * (1.f / 128.f) + RMS_EPS);
;     bf16_t* mp = k.MIX + (size_t)(tokb + k.pt) * DM + k.h * 128 + 32 * k.pseg;
; #pragma unroll
;     for (int i = 0; i < 4; ++i) { u32x4 res;
; #pragma unroll
;         for (int j = 0; j < 4; ++j) { const int e = 8 * i + 2 * j;
;             const float a0 = lo_bf(ov4[i][j]) * rs * gmL[e] * lo_bf(zz[i][j]), a1 = hi_bf(ov4[i][j]) * rs * gmL[e + 1] * hi_bf(zz[i][j]); res[j] = pk2(a0, a1); }
;         *(u32x4*)(mp + 8 * i) = res; }
	v_add_f32_e32 v18, v18, v19
	s_nop 1
	v_mov_b32_dpp v19, v18 quad_perm:[2,3,0,1] row_mask:0xf bank_mask:0xf
	s_lshl_b32 s43, s42, 1
	s_add_u32 s14, s4, s43
	s_addc_u32 s15, s5, 0
	s_add_u32 s40, s6, s43
	s_waitcnt lgkmcnt(0)
	v_add_f32_e32 v18, v18, v19
	v_fmamk_f32 v18, v18, 0x3c000000, v231
	v_rsq_f32_e32 v22, v18
	s_addc_u32 s41, s7, 0
	v_pk_mul_f32 v[18:19], v[22:23], v[198:199] op_sel_hi:[0,1]
	v_pk_mul_f32 v[20:21], v[22:23], v[188:189] op_sel_hi:[0,1]
	v_pk_mul_f32 v[18:19], v[24:25], v[18:19]
	v_pk_mul_f32 v[20:21], v[26:27], v[20:21]
	v_pk_mul_f32 v[18:19], v[18:19], v[202:203]
	v_pk_mul_f32 v[20:21], v[20:21], v[192:193]
	v_cvt_pk_bf16_f32 v18, v18, v19
	v_cvt_pk_bf16_f32 v19, v20, v21
	v_pk_mul_f32 v[20:21], v[22:23], v[52:53] op_sel_hi:[0,1]
	v_pk_mul_f32 v[24:25], v[22:23], v[48:49] op_sel_hi:[0,1]
	v_pk_mul_f32 v[20:21], v[28:29], v[20:21]
	v_pk_mul_f32 v[24:25], v[30:31], v[24:25]
	v_pk_mul_f32 v[20:21], v[20:21], v[56:57]
	v_pk_mul_f32 v[24:25], v[24:25], v[126:127]
	v_cvt_pk_bf16_f32 v20, v20, v21
	v_cvt_pk_bf16_f32 v21, v24, v25
	global_store_dwordx4 v[46:47], v[18:21], off
	v_pk_mul_f32 v[24:25], v[22:23], v[128:129] op_sel_hi:[0,1]
	v_pk_mul_f32 v[24:25], v[38:39], v[24:25]
	v_pk_mul_f32 v[18:19], v[22:23], v[218:219] op_sel_hi:[0,1]
	v_pk_mul_f32 v[20:21], v[22:23], v[212:213] op_sel_hi:[0,1]
	v_pk_mul_f32 v[18:19], v[32:33], v[18:19]
	v_pk_mul_f32 v[20:21], v[34:35], v[20:21]
	v_pk_mul_f32 v[18:19], v[18:19], v[220:221]
	v_pk_mul_f32 v[20:21], v[20:21], v[216:217]
	v_cvt_pk_bf16_f32 v18, v18, v19
	v_cvt_pk_bf16_f32 v19, v20, v21
	v_pk_mul_f32 v[20:21], v[22:23], v[208:209] op_sel_hi:[0,1]
	v_pk_mul_f32 v[20:21], v[36:37], v[20:21]
	v_pk_mul_f32 v[24:25], v[24:25], v[122:123]
	v_pk_mul_f32 v[20:21], v[20:21], v[210:211]
	v_add_u32_e32 v188, 64, v150
	v_cvt_pk_bf16_f32 v20, v20, v21
	v_cvt_pk_bf16_f32 v21, v24, v25
	global_store_dwordx4 v[46:47], v[18:21], off offset:16
	v_ashrrev_i32_e32 v189, 31, v188
	v_lshl_add_u64 v[30:31], s[40:41], 0, v[140:141]
	v_pk_mul_f32 v[18:19], v[22:23], v[224:225] op_sel_hi:[0,1]
	v_pk_mul_f32 v[14:15], v[18:19], v[14:15]
	v_pk_mul_f32 v[18:19], v[22:23], v[124:125] op_sel_hi:[0,1]
	v_pk_mul_f32 v[16:17], v[18:19], v[16:17]
	v_lshlrev_b32_e32 v18, 16, v119
	v_and_b32_e32 v19, 0xffff0000, v119
	v_pk_mul_f32 v[14:15], v[14:15], v[228:229]
	v_pk_mul_f32 v[16:17], v[16:17], v[18:19]
	v_cvt_pk_bf16_f32 v14, v14, v15
	v_cvt_pk_bf16_f32 v15, v16, v17
	v_mov_b32_e32 v16, v10
	v_mov_b32_e32 v17, v12
	v_pk_mul_f32 v[20:21], v[22:23], v[16:17] op_sel_hi:[0,1]
	v_mov_b32_e32 v12, v11
	v_pk_mul_f32 v[10:11], v[22:23], v[12:13] op_sel_hi:[0,1]
	v_lshlrev_b32_e32 v12, 16, v121
	v_and_b32_e32 v13, 0xffff0000, v121
	s_waitcnt lgkmcnt(0)
	v_pk_mul_f32 v[16:17], v[20:21], v[130:131]
	v_lshlrev_b32_e32 v20, 16, v120
	v_and_b32_e32 v21, 0xffff0000, v120
	v_pk_mul_f32 v[10:11], v[10:11], v[132:133]
	v_pk_mul_f32 v[16:17], v[16:17], v[20:21]
	v_pk_mul_f32 v[10:11], v[10:11], v[12:13]
	v_cvt_pk_bf16_f32 v16, v16, v17
	v_cvt_pk_bf16_f32 v17, v10, v11
	v_mov_b32_e32 v10, v6
	v_mov_b32_e32 v11, v8
	global_store_dwordx4 v[46:47], v[14:17], off offset:32
	v_mov_b32_e32 v8, v7
	v_pk_mul_f32 v[8:9], v[22:23], v[8:9] op_sel_hi:[0,1]
	v_pk_mul_f32 v[14:15], v[22:23], v[10:11] op_sel_hi:[0,1]
	v_lshl_add_u64 v[30:31], v[30:31], 0, v[0:1]
	v_add_u32_e32 v150, 0x80, v150
	s_waitcnt lgkmcnt(0)
	v_pk_mul_f32 v[10:11], v[14:15], v[194:195]
	v_lshlrev_b32_e32 v14, 16, v114
	v_and_b32_e32 v15, 0xffff0000, v114
	v_pk_mul_f32 v[10:11], v[10:11], v[14:15]
	v_pk_mul_f32 v[8:9], v[8:9], v[196:197]
	v_cvt_pk_bf16_f32 v6, v10, v11
	v_lshlrev_b32_e32 v10, 16, v115
	v_and_b32_e32 v11, 0xffff0000, v115
	v_pk_mul_f32 v[8:9], v[8:9], v[10:11]
	v_lshl_add_u64 v[14:15], s[40:41], 0, v[136:137]
	v_cvt_pk_bf16_f32 v7, v8, v9
	v_mov_b32_e32 v8, v2
	v_mov_b32_e32 v9, v4
	v_pk_mul_f32 v[12:13], v[22:23], v[8:9] op_sel_hi:[0,1]
	v_mov_b32_e32 v4, v3
	v_pk_mul_f32 v[2:3], v[22:23], v[4:5] op_sel_hi:[0,1]
	v_lshlrev_b32_e32 v4, 16, v117
	v_and_b32_e32 v5, 0xffff0000, v117
	s_waitcnt lgkmcnt(0)
	v_pk_mul_f32 v[8:9], v[12:13], v[232:233]
	v_lshlrev_b32_e32 v12, 16, v116
	v_and_b32_e32 v13, 0xffff0000, v116
	v_pk_mul_f32 v[2:3], v[2:3], v[234:235]
	v_pk_mul_f32 v[8:9], v[8:9], v[12:13]
	v_pk_mul_f32 v[2:3], v[2:3], v[4:5]
	v_cvt_pk_bf16_f32 v8, v8, v9
	v_cvt_pk_bf16_f32 v9, v2, v3
	v_add_u32_e32 v2, 64, v188
	v_ashrrev_i32_e32 v3, 31, v2
	v_lshlrev_b64 v[2:3], 10, v[2:3]
	global_store_dwordx4 v[46:47], v[6:9], off offset:48
	v_lshl_add_u64 v[2:3], v[152:153], 0, v[2:3]
	global_load_dwordx4 v[114:117], v[2:3], off offset:48
	global_load_dwordx4 v[118:121], v[2:3], off offset:32
	global_load_dwordx4 v[122:125], v[2:3], off offset:16
	global_load_dwordx4 v[126:129], v[2:3], off
	v_lshl_add_u64 v[2:3], s[14:15], 0, v[134:135]
	v_lshl_add_u64 v[6:7], s[40:41], 0, v[134:135]
	v_lshl_add_u64 v[2:3], v[2:3], 0, v[0:1]
	v_lshl_add_u64 v[6:7], v[6:7], 0, v[0:1]
	global_load_dwordx4 v[2:5], v[2:3], off
	v_lshl_add_u64 v[14:15], v[14:15], 0, v[0:1]
	global_load_dwordx4 v[10:13], v[6:7], off
	v_lshl_add_u64 v[6:7], s[14:15], 0, v[136:137]
	v_lshl_add_u64 v[6:7], v[6:7], 0, v[0:1]
	global_load_dwordx4 v[6:9], v[6:7], off
	v_lshl_add_u64 v[22:23], s[40:41], 0, v[138:139]
	global_load_dwordx4 v[18:21], v[14:15], off
	v_lshl_add_u64 v[14:15], s[14:15], 0, v[138:139]
	v_lshl_add_u64 v[14:15], v[14:15], 0, v[0:1]
	v_lshl_add_u64 v[22:23], v[22:23], 0, v[0:1]
	global_load_dwordx4 v[14:17], v[14:15], off
	s_mov_b32 s40, s24
	global_load_dwordx4 v[26:29], v[22:23], off
	v_lshl_add_u64 v[22:23], s[14:15], 0, v[140:141]
	s_add_u32 s14, s8, s43
	s_addc_u32 s15, s9, 0
	v_lshl_add_u64 v[34:35], s[14:15], 0, v[142:143]
	v_lshl_add_u64 v[38:39], s[14:15], 0, v[144:145]
	v_lshl_add_u64 v[42:43], s[14:15], 0, v[146:147]
	v_lshl_add_u64 v[46:47], s[14:15], 0, v[148:149]
	s_add_u32 s14, s10, s42
	s_addc_u32 s15, s11, 0
	v_lshl_add_u64 v[50:51], s[14:15], 0, v[142:143]
	v_lshl_add_u64 v[54:55], s[14:15], 0, v[144:145]
	v_lshl_add_u64 v[22:23], v[22:23], 0, v[0:1]
	v_lshl_add_u64 v[34:35], v[34:35], 0, v[156:157]
	v_lshl_add_u64 v[38:39], v[38:39], 0, v[156:157]
	v_lshl_add_u64 v[42:43], v[42:43], 0, v[156:157]
	v_lshl_add_u64 v[46:47], v[46:47], 0, v[156:157]
	v_lshl_add_u64 v[50:51], v[50:51], 0, v[156:157]
	v_lshl_add_u64 v[54:55], v[54:55], 0, v[156:157]
	global_load_dwordx4 v[22:25], v[22:23], off
	s_cmpk_gt_u32 s24, 0x7d
	global_load_dwordx4 v[30:33], v[30:31], off
	s_waitcnt vmcnt(16)
; #define LAS __attribute__((address_space(3)))
; DI void sh_store(const ScanH& k, int bf, const u32x4 (&st)[14]) {
;     LAS unsigned char* B_ = k.lds + bf * SC_BUF; const int ht = k.ht;
; #pragma unroll
;     for (int i = 0; i < 4; ++i) { const int id = ht + 256 * i, r = id >> 4, cc = id & 15;
;         *(LAS u32x2*)(B_ + SC_W + r * 264 + cc * 16) = (u32x2){st[i].x, st[i].y}; *(LAS u32x2*)(B_ + SC_W + r * 264 + cc * 16 + 8) = (u32x2){st[i].z, st[i].w};
;         *(LAS u32x2*)(B_ + SC_Q + r * 264 + cc * 16) = (u32x2){st[4 + i].x, st[4 + i].y}; *(LAS u32x2*)(B_ + SC_Q + r * 264 + cc * 16 + 8) = (u32x2){st[4 + i].z, st[4 + i].w}; }
; #pragma unroll
;     for (int i = 0; i < 4; ++i) { const int id = ht + 256 * i, r = id >> 3, cc = id & 7;
;         *(LAS u32x2*)(B_ + SC_K + r * 136 + cc * 16) = (u32x2){st[8 + i].x, st[8 + i].y}; *(LAS u32x2*)(B_ + SC_K + r * 136 + cc * 16 + 8) = (u32x2){st[8 + i].z, st[8 + i].w}; }
; #pragma unroll
;     for (int i = 0; i < 2; ++i) { const int id = ht + 256 * i, r = id >> 3, cc = id & 7;
;         *(LAS u32x2*)(B_ + SC_A + r * 136 + cc * 16) = (u32x2){st[12 + i].x, st[12 + i].y}; *(LAS u32x2*)(B_ + SC_A + r * 136 + cc * 16 + 8) = (u32x2){st[12 + i].z, st[12 + i].w}; }
; }
; DI void scan_helper_step(const ScanH& k, int n, u32x4 (&stL)[14], const u32x4 (&stS)[14]) {
;     LAS unsigned char* lds = k.lds; const int bf = n & 1, tokb = k.b * SEQ + n * 64;
;     u32x4 zz[4];
;     { const bf16_t* zp = k.Zg + (size_t)(tokb + k.pt) * 512 + k.h * 128 + 32 * k.pseg;
; #pragma unroll
;       for (int i = 0; i < 4; ++i) zz[i] = *(const u32x4*)(zp + 8 * i); }
;     sh_load(k, n + 2 < 128 ? n + 2 : 127, stL);
;     sh_store(k, bf ^ 1, stS);
;     SC_RAW_BARRIER();
;     const LAS unsigned char* ob = lds + SC_O + bf * SC_OSZ + k.pt * 272 + k.pseg * 64;
;     const LAS float* gmL = (const LAS float*)(lds + SC_O + 2 * SC_OSZ + 512) + 32 * k.pseg;
;     u32x4 ov4[4];
; #pragma unroll
;     for (int i = 0; i < 4; ++i) ov4[i] = *(const LAS u32x4*)(ob + 16 * i);
;     float ss = 0.f;
; #pragma unroll
;     for (int i = 0; i < 4; ++i)
; #pragma unroll
;         for (int j = 0; j < 4; ++j) { const float a = lo_bf(ov4[i][j]), b2 = hi_bf(ov4[i][j]); ss += a * a + b2 * b2; }
;     ss += __shfl_xor(ss, 1); ss += __shfl_xor(ss, 2);
;     const float rs = __builtin_amdgcn_rsqf(ss * (1.f / 128.f) + RMS_EPS);
	v_lshlrev_b32_e32 v228, 16, v240
	global_load_dwordx4 v[34:37], v[34:35], off
	v_and_b32_e32 v229, 0xffff0000, v240
	global_load_dwordx4 v[38:41], v[38:39], off
	v_lshlrev_b32_e32 v192, 16, v249
	global_load_dwordx4 v[42:45], v[42:43], off
	v_and_b32_e32 v193, 0xffff0000, v249
	global_load_dwordx4 v[46:49], v[46:47], off
	v_lshlrev_b32_e32 v202, 16, v248
	global_load_dwordx4 v[50:53], v[50:51], off
	v_and_b32_e32 v203, 0xffff0000, v248
	global_load_dwordx4 v[54:57], v[54:55], off
	s_waitcnt vmcnt(22)
	ds_write2_b64 v159, v[58:59], v[60:61] offset1:1
	ds_write2_b64 v160, v[62:63], v[64:65] offset1:1
	ds_write2_b64 v162, v[66:67], v[68:69] offset1:1
	ds_write2_b64 v163, v[70:71], v[72:73] offset1:1
	ds_write2_b64 v165, v[74:75], v[76:77] offset1:1
	ds_write2_b64 v166, v[78:79], v[80:81] offset1:1
	ds_write2_b64 v168, v[82:83], v[84:85] offset1:1
	ds_write2_b64 v169, v[86:87], v[88:89] offset1:1
	ds_write2_b64 v171, v[90:91], v[92:93] offset1:1
	ds_write2_b64 v173, v[94:95], v[96:97] offset1:1
	ds_write2_b64 v175, v[98:99], v[100:101] offset1:1
	ds_write2_b64 v177, v[102:103], v[104:105] offset1:1
	ds_write2_b64 v178, v[106:107], v[108:109] offset1:1
	ds_write2_b64 v179, v[110:111], v[112:113] offset1:1
	s_waitcnt lgkmcnt(0)
	s_barrier
	ds_read_b128 v[58:61], v185
	ds_read_b128 v[62:65], v185 offset:16
	ds_read_b128 v[66:69], v185 offset:32
	ds_read_b128 v[70:73], v185 offset:48
	v_lshlrev_b32_e32 v112, 16, v250
	s_waitcnt lgkmcnt(3)
	v_lshlrev_b32_e32 v198, 16, v58
	v_and_b32_e32 v199, 0xffff0000, v58
	s_waitcnt lgkmcnt(1)
	v_and_b32_e32 v87, 0xffff0000, v69
	v_and_b32_e32 v86, 0xffff0000, v68
	v_lshlrev_b32_e32 v85, 16, v69
	v_lshlrev_b32_e32 v84, 16, v68
	v_pk_mul_f32 v[68:69], v[86:87], v[86:87]
	s_waitcnt lgkmcnt(0)
	v_and_b32_e32 v93, 0xffff0000, v71
	v_and_b32_e32 v92, 0xffff0000, v70
	v_pk_fma_f32 v[88:89], v[84:85], v[84:85], v[68:69]
	v_lshlrev_b32_e32 v91, 16, v71
	v_lshlrev_b32_e32 v90, 16, v70
	v_pk_mul_f32 v[68:69], v[92:93], v[92:93]
	v_and_b32_e32 v99, 0xffff0000, v73
	v_and_b32_e32 v98, 0xffff0000, v72
	v_pk_fma_f32 v[94:95], v[90:91], v[90:91], v[68:69]
	v_lshlrev_b32_e32 v97, 16, v73
	v_lshlrev_b32_e32 v96, 16, v72
	v_pk_mul_f32 v[68:69], v[98:99], v[98:99]
	v_lshlrev_b32_e32 v108, 16, v60
	v_pk_fma_f32 v[100:101], v[96:97], v[96:97], v[68:69]
	v_lshlrev_b64 v[68:69], 11, v[188:189]
	v_lshlrev_b32_e32 v188, 16, v59
	v_and_b32_e32 v189, 0xffff0000, v59
	v_and_b32_e32 v109, 0xffff0000, v60
	v_pk_mul_f32 v[190:191], v[188:189], v[188:189]
	v_pk_mul_f32 v[200:201], v[198:199], v[198:199]
	v_lshlrev_b32_e32 v104, 16, v61
	v_and_b32_e32 v105, 0xffff0000, v61
	v_pk_mul_f32 v[110:111], v[108:109], v[108:109]
	v_add_f32_e32 v240, v190, v191
	v_add_f32_e32 v151, v200, v201
	v_pk_mul_f32 v[106:107], v[104:105], v[104:105]
	v_lshlrev_b32_e32 v218, 16, v62
	v_and_b32_e32 v219, 0xffff0000, v62
	v_add_f32_e32 v240, v151, v240
	v_add_f32_e32 v110, v110, v111
	v_lshlrev_b32_e32 v212, 16, v63
	v_and_b32_e32 v213, 0xffff0000, v63
	v_pk_mul_f32 v[62:63], v[218:219], v[218:219]
	v_add_f32_e32 v110, v110, v240
	v_add_f32_e32 v106, v106, v107
	v_lshlrev_b32_e32 v208, 16, v64
	v_and_b32_e32 v209, 0xffff0000, v64
	v_pk_mul_f32 v[214:215], v[212:213], v[212:213]
	v_add_f32_e32 v106, v106, v110
	v_add_f32_e32 v62, v62, v63
	v_and_b32_e32 v113, 0xffff0000, v250
	v_lshlrev_b32_e32 v248, 16, v251
	v_and_b32_e32 v249, 0xffff0000, v251
	v_lshlrev_b32_e32 v250, 16, v65
	v_and_b32_e32 v251, 0xffff0000, v65
	v_pk_mul_f32 v[64:65], v[208:209], v[208:209]
	v_add_f32_e32 v62, v62, v106
	v_add_f32_e32 v63, v214, v215
	v_pk_mul_f32 v[204:205], v[250:251], v[250:251]
	v_lshlrev_b32_e32 v224, 16, v66
	v_and_b32_e32 v225, 0xffff0000, v66
	v_add_f32_e32 v62, v63, v62
	v_add_f32_e32 v63, v64, v65
	v_lshlrev_b32_e32 v210, 16, v246
	v_and_b32_e32 v211, 0xffff0000, v246
	v_lshlrev_b32_e32 v216, 16, v245
	v_and_b32_e32 v217, 0xffff0000, v245
	v_lshlrev_b32_e32 v220, 16, v244
	v_and_b32_e32 v221, 0xffff0000, v244
	v_lshlrev_b32_e32 v244, 16, v247
	v_and_b32_e32 v245, 0xffff0000, v247
	v_lshlrev_b32_e32 v246, 16, v67
	v_and_b32_e32 v247, 0xffff0000, v67
	v_pk_mul_f32 v[66:67], v[224:225], v[224:225]
	v_add_f32_e32 v62, v63, v62
	v_add_f32_e32 v63, v204, v205
	v_pk_mul_f32 v[222:223], v[246:247], v[246:247]
	v_add_f32_e32 v62, v63, v62
	v_add_f32_e32 v63, v66, v67
	v_add_f32_e32 v62, v63, v62
	v_add_f32_e32 v63, v222, v223
	v_add_f32_e32 v62, v63, v62
	v_add_f32_e32 v62, v88, v62
	v_add_f32_e32 v62, v89, v62
	v_add_f32_e32 v62, v94, v62
	v_add_f32_e32 v62, v95, v62
	v_add_f32_e32 v62, v100, v62
	v_add_f32_e32 v62, v101, v62
	s_nop 1
	v_mov_b32_dpp v63, v62 quad_perm:[1,0,3,2] row_mask:0xf bank_mask:0xf
	v_lshl_add_u64 v[102:103], v[154:155], 0, v[68:69]
	ds_read_b128 v[68:71], v184
	ds_read_b128 v[72:75], v184 offset:16
	ds_read_b128 v[76:79], v184 offset:32
	ds_read_b128 v[80:83], v184 offset:48
	ds_read_b128 v[58:61], v184 offset:64
	ds_read_b128 v[130:133], v184 offset:80
	ds_read_b128 v[194:197], v184 offset:96
	ds_read_b128 v[232:235], v184 offset:112
	s_waitcnt lgkmcnt(5)
; DI unsigned pk2(float lo, float hi) { f32x2 v = {lo, hi}; bf16x2_t b = __builtin_convertvector(v, bf16x2_t); return __builtin_bit_cast(unsigned, b); }
; DI float lo_bf(unsigned u) { return __uint_as_float(u << 16); }
; DI float hi_bf(unsigned u) { return __uint_as_float(u & 0xffff0000u); }
; DI void scan_helper_step(const ScanH& k, int n, u32x4 (&stL)[14], const u32x4 (&stS)[14]) {
;     ...
;     const float rs = __builtin_amdgcn_rsqf(ss * (1.f / 128.f) + RMS_EPS);
;     bf16_t* mp = k.MIX + (size_t)(tokb + k.pt) * DM + k.h * 128 + 32 * k.pseg;
; #pragma unroll
;     for (int i = 0; i < 4; ++i) { u32x4 res;
; #pragma unroll
;         for (int j = 0; j < 4; ++j) { const int e = 8 * i + 2 * j;
;             const float a0 = lo_bf(ov4[i][j]) * rs * gmL[e] * lo_bf(zz[i][j]), a1 = hi_bf(ov4[i][j]) * rs * gmL[e + 1] * hi_bf(zz[i][j]); res[j] = pk2(a0, a1); }
;         *(u32x4*)(mp + 8 * i) = res; }
; DI void scan_item(LAS unsigned char* lds, const Ctx& c, int l, int bh) {
;     ...
;         for (int n = 0; n < 128; n += 2) {
;             scan_helper_step(k, n, stA, stB);
;             scan_helper_step(k, n + 1, stB, stA);
;         }
	v_add_f32_e32 v62, v62, v63
	s_nop 1
	v_mov_b32_dpp v63, v62 quad_perm:[2,3,0,1] row_mask:0xf bank_mask:0xf
	s_waitcnt lgkmcnt(0)
	v_add_f32_e32 v62, v62, v63
	v_fmamk_f32 v62, v62, 0x3c000000, v231
	v_rsq_f32_e32 v66, v62
	s_nop 0
	v_pk_mul_f32 v[62:63], v[66:67], v[198:199] op_sel_hi:[0,1]
	v_pk_mul_f32 v[64:65], v[66:67], v[188:189] op_sel_hi:[0,1]
	v_pk_mul_f32 v[62:63], v[68:69], v[62:63]
	v_pk_mul_f32 v[64:65], v[70:71], v[64:65]
	v_pk_mul_f32 v[62:63], v[62:63], v[202:203]
	v_pk_mul_f32 v[64:65], v[64:65], v[192:193]
	v_cvt_pk_bf16_f32 v62, v62, v63
	v_cvt_pk_bf16_f32 v63, v64, v65
	v_pk_mul_f32 v[64:65], v[66:67], v[108:109] op_sel_hi:[0,1]
	v_pk_mul_f32 v[68:69], v[66:67], v[104:105] op_sel_hi:[0,1]
	v_pk_mul_f32 v[64:65], v[72:73], v[64:65]
	v_pk_mul_f32 v[68:69], v[74:75], v[68:69]
	v_pk_mul_f32 v[64:65], v[64:65], v[112:113]
	v_pk_mul_f32 v[68:69], v[68:69], v[248:249]
	v_cvt_pk_bf16_f32 v64, v64, v65
	v_cvt_pk_bf16_f32 v65, v68, v69
	global_store_dwordx4 v[102:103], v[62:65], off
	v_pk_mul_f32 v[68:69], v[66:67], v[250:251] op_sel_hi:[0,1]
	v_pk_mul_f32 v[68:69], v[82:83], v[68:69]
	v_pk_mul_f32 v[62:63], v[66:67], v[218:219] op_sel_hi:[0,1]
	v_pk_mul_f32 v[64:65], v[66:67], v[212:213] op_sel_hi:[0,1]
	v_pk_mul_f32 v[62:63], v[76:77], v[62:63]
	v_pk_mul_f32 v[64:65], v[78:79], v[64:65]
	v_pk_mul_f32 v[62:63], v[62:63], v[220:221]
	v_pk_mul_f32 v[64:65], v[64:65], v[216:217]
	v_cvt_pk_bf16_f32 v62, v62, v63
	v_cvt_pk_bf16_f32 v63, v64, v65
	v_pk_mul_f32 v[64:65], v[66:67], v[208:209] op_sel_hi:[0,1]
	v_pk_mul_f32 v[64:65], v[80:81], v[64:65]
	v_pk_mul_f32 v[68:69], v[68:69], v[244:245]
	v_pk_mul_f32 v[64:65], v[64:65], v[210:211]
	s_nop 0
	v_cvt_pk_bf16_f32 v64, v64, v65
	v_cvt_pk_bf16_f32 v65, v68, v69
	global_store_dwordx4 v[102:103], v[62:65], off offset:16
	s_nop 1
	v_pk_mul_f32 v[62:63], v[66:67], v[224:225] op_sel_hi:[0,1]
	v_pk_mul_f32 v[58:59], v[58:59], v[62:63]
	v_pk_mul_f32 v[62:63], v[66:67], v[246:247] op_sel_hi:[0,1]
	v_pk_mul_f32 v[60:61], v[62:63], v[60:61]
	v_lshlrev_b32_e32 v62, 16, v241
	v_and_b32_e32 v63, 0xffff0000, v241
	v_pk_mul_f32 v[58:59], v[58:59], v[228:229]
	v_pk_mul_f32 v[60:61], v[60:61], v[62:63]
	v_cvt_pk_bf16_f32 v58, v58, v59
	v_cvt_pk_bf16_f32 v59, v60, v61
	v_mov_b32_e32 v60, v84
	v_mov_b32_e32 v61, v86
	v_pk_mul_f32 v[64:65], v[66:67], v[60:61] op_sel_hi:[0,1]
	v_mov_b32_e32 v86, v85
	s_waitcnt lgkmcnt(0)
	v_pk_mul_f32 v[60:61], v[64:65], v[130:131]
	v_lshlrev_b32_e32 v64, 16, v242
	v_and_b32_e32 v65, 0xffff0000, v242
	v_pk_mul_f32 v[60:61], v[60:61], v[64:65]
	v_pk_mul_f32 v[64:65], v[66:67], v[86:87] op_sel_hi:[0,1]
	v_pk_mul_f32 v[62:63], v[64:65], v[132:133]
	v_lshlrev_b32_e32 v64, 16, v243
	v_and_b32_e32 v65, 0xffff0000, v243
	v_pk_mul_f32 v[62:63], v[62:63], v[64:65]
	v_cvt_pk_bf16_f32 v60, v60, v61
	v_cvt_pk_bf16_f32 v61, v62, v63
	global_store_dwordx4 v[102:103], v[58:61], off offset:32
	s_nop 1
	v_mov_b32_e32 v58, v90
	v_mov_b32_e32 v59, v92
	v_pk_mul_f32 v[62:63], v[66:67], v[58:59] op_sel_hi:[0,1]
	v_mov_b32_e32 v92, v91
	s_waitcnt lgkmcnt(0)
	v_pk_mul_f32 v[58:59], v[62:63], v[194:195]
	v_lshlrev_b32_e32 v62, 16, v236
	v_and_b32_e32 v63, 0xffff0000, v236
	v_pk_mul_f32 v[58:59], v[58:59], v[62:63]
	v_pk_mul_f32 v[62:63], v[66:67], v[92:93] op_sel_hi:[0,1]
	v_pk_mul_f32 v[60:61], v[62:63], v[196:197]
	v_lshlrev_b32_e32 v62, 16, v237
	v_and_b32_e32 v63, 0xffff0000, v237
	v_pk_mul_f32 v[60:61], v[60:61], v[62:63]
	v_cvt_pk_bf16_f32 v58, v58, v59
	v_cvt_pk_bf16_f32 v59, v60, v61
	v_mov_b32_e32 v60, v96
	v_mov_b32_e32 v61, v98
	v_pk_mul_f32 v[64:65], v[66:67], v[60:61] op_sel_hi:[0,1]
	v_mov_b32_e32 v98, v97
	s_waitcnt lgkmcnt(0)
	v_pk_mul_f32 v[60:61], v[64:65], v[232:233]
	v_lshlrev_b32_e32 v64, 16, v238
	v_and_b32_e32 v65, 0xffff0000, v238
	v_pk_mul_f32 v[60:61], v[60:61], v[64:65]
	v_pk_mul_f32 v[64:65], v[66:67], v[98:99] op_sel_hi:[0,1]
	v_pk_mul_f32 v[62:63], v[64:65], v[234:235]
	v_lshlrev_b32_e32 v64, 16, v239
	v_and_b32_e32 v65, 0xffff0000, v239
	v_pk_mul_f32 v[62:63], v[62:63], v[64:65]
	v_cvt_pk_bf16_f32 v60, v60, v61
	v_cvt_pk_bf16_f32 v61, v62, v63
	global_store_dwordx4 v[102:103], v[58:61], off offset:48
	s_cbranch_scc0 .LBB0_198
	s_waitcnt vmcnt(0)
	s_setprio 0
	v_mov_b32_e32 v130, v1
	v_mov_b32_e32 v131, v1
	v_mov_b32_e32 v132, v1
	v_mov_b32_e32 v133, v1
	v_mov_b64_e32 v[194:195], 0x200
	v_mov_b64_e32 v[196:197], 0x1ff
	v_mov_b64_e32 v[232:233], 0x17f
	v_mov_b32_e32 v234, 0xc00
	v_mov_b32_e32 v235, 1
	v_mov_b64_e32 v[250:251], 0xaff
